# LayerNorm phases 0/1: next-row loads prefetched one row ahead
# speedup vs baseline: 1.0274x; 1.0009x over previous
; DEVI int opaque_tid() { int t = __builtin_amdgcn_workitem_id_x(); asm volatile("" : "+v"(t)); return t; }
; DEVI char* opaque_ptr(char* p) { asm volatile("" : "+s"(p)); return p; }
; DEVI void phase_ln(const Params& p, int L, int which) {
;   const int lane = opaque_tid() & 63, wid = opaque_tid() >> 6;
;   const int gw = blockIdx.x * 4 + wid, nw = gridDim.x * 4;
;   const float* g = p.in[22] + (L * 3 + which) * 1024;
;   const float* bb = p.in[23] + (L * 3 + which) * 1024;
;   char* ws = opaque_ptr(p.ws);
;   bf16* xb = (bf16*)(ws + OFF_XB);
;   float* stats = (float*)(ws + OFF_STATS);
;   const bool final_out = (L == 3 && which == 2);
;   const f32x4 g0 = *(const f32x4*)(g + lane * 4), g1 = *(const f32x4*)(g + 256 + lane * 4), g2 = *(const f32x4*)(g + 512 + lane * 4), g3 = *(const f32x4*)(g + 768 + lane * 4);
;   const f32x4 b0 = *(const f32x4*)(bb + lane * 4), b1 = *(const f32x4*)(bb + 256 + lane * 4), b2 = *(const f32x4*)(bb + 512 + lane * 4), b3 = *(const f32x4*)(bb + 768 + lane * 4);
;   for (int row = gw; row < T_TOK; row += nw) {
;     float* xr = p.out + (long)row * 1024;
;     f32x4 v0 = *(const f32x4*)(xr + lane * 4), v1 = *(const f32x4*)(xr + 256 + lane * 4);
.LBB0_1562:
	s_or_b64 exec, exec, s[8:9]
	v_mov_b32_e32 v2, v154
	v_mov_b32_e32 v0, v154
	s_waitcnt lgkmcnt(0)
	s_barrier
	v_readlane_b32 s6, v250, 9
	v_ashrrev_i32_e32 v0, 6, v0
	s_mov_b32 s13, s81
	v_readlane_b32 s60, v250, 17
	v_add_u32_e32 v50, s6, v0
	s_lshl_b64 s[6:7], s[12:13], 2
	v_readlane_b32 s72, v250, 29
	v_readlane_b32 s73, v250, 30
	s_add_u32 s16, s72, s6
	v_readlane_b32 s74, v250, 31
	s_addc_u32 s17, s73, s7
	v_readlane_b32 s75, v250, 32
	s_add_u32 s18, s74, s6
	s_mov_b32 s6, 0x8000
	s_addc_u32 s19, s75, s7
	s_mov_b64 s[36:37], s[90:91]
	v_cmp_gt_i32_e32 vcc, s6, v50
	v_readlane_b32 s61, v250, 18
	v_readlane_b32 s62, v250, 19
	v_readlane_b32 s63, v250, 20
	v_readlane_b32 s64, v250, 21
	v_readlane_b32 s65, v250, 22
	v_readlane_b32 s66, v250, 23
	v_readlane_b32 s67, v250, 24
	v_readlane_b32 s68, v250, 25
	v_readlane_b32 s69, v250, 26
	v_readlane_b32 s70, v250, 27
	v_readlane_b32 s71, v250, 28
	s_and_saveexec_b64 s[8:9], vcc
	s_cbranch_execz .LBB0_1567
	v_and_b32_e32 v36, 63, v2
	v_lshlrev_b32_e32 v37, 4, v36
	global_load_dwordx4 v[2:5], v37, s[16:17]
	global_load_dwordx4 v[6:9], v37, s[16:17] offset:1024
	global_load_dwordx4 v[10:13], v37, s[16:17] offset:2048
	global_load_dwordx4 v[14:17], v37, s[16:17] offset:3072
	global_load_dwordx4 v[18:21], v37, s[18:19]
	global_load_dwordx4 v[22:25], v37, s[18:19] offset:1024
	global_load_dwordx4 v[26:29], v37, s[18:19] offset:2048
	global_load_dwordx4 v[30:33], v37, s[18:19] offset:3072
	v_ashrrev_i32_e32 v51, 31, v50
	v_lshlrev_b64 v[34:35], 11, v[50:51]
	v_readlane_b32 s6, v249, 41
	v_lshl_or_b32 v34, v36, 3, v34
	v_lshl_add_u64 v[34:35], s[36:37], 0, v[34:35]
	v_lshl_add_u32 v52, v0, 1, s6
	s_mov_b64 s[6:7], 0x22bc000
	v_lshl_add_u64 v[54:55], v[34:35], 0, s[6:7]
	v_lshlrev_b64 v[34:35], 12, v[50:51]
	v_readlane_b32 s6, v249, 45
	s_add_u32 s38, s36, 0x1d6bc000
	v_or_b32_e32 v34, v34, v37
	v_readlane_b32 s7, v249, 46
	s_addc_u32 s39, s37, 0
	v_cmp_eq_u32_e32 vcc, 0, v36
	v_lshl_add_u64 v[56:57], s[6:7], 0, v[34:35]
	global_load_dwordx4 v[232:235], v[56:57], off offset:-3072
	global_load_dwordx4 v[236:239], v[56:57], off offset:-2048
	global_load_dwordx4 v[240:243], v[56:57], off offset:-1024
	global_load_dwordx4 v[244:247], v[56:57], off
	s_mov_b64 s[40:41], 0
	s_branch .LBB0_1565

; DEVI void phase_ln(const Params& p, int L, int which) {
;     ...
;   for (int row = gw; row < T_TOK; row += nw) {
;     float* xr = p.out + (long)row * 1024;
;     f32x4 v0 = *(const f32x4*)(xr + lane * 4), v1 = *(const f32x4*)(xr + 256 + lane * 4);
;     f32x4 v2 = *(const f32x4*)(xr + 512 + lane * 4), v3 = *(const f32x4*)(xr + 768 + lane * 4);
;     f32x4 sv = v0 + v1 + v2 + v3;
;     float s = sv[0] + sv[1] + sv[2] + sv[3];
;     s = wave_sum(s);
;     const float mu = s * (1.f / 1024.f);
;     v0 -= mu; v1 -= mu; v2 -= mu; v3 -= mu;
;     f32x4 qv = v0 * v0 + v1 * v1 + v2 * v2 + v3 * v3;
;     float q = qv[0] + qv[1] + qv[2] + qv[3];
;     q = wave_sum(q);
;     const float rstd = rsqrtf(q * (1.f / 1024.f) + 1e-5f);
;     if (lane == 0) { stats[row * 2] = mu; stats[row * 2 + 1] = rstd; }
.LBB0_1565:
	s_waitcnt vmcnt(0)
	v_readlane_b32 s36, v249, 50
	v_readlane_b32 s6, v249, 52
	v_readlane_b32 s7, v249, 53
	v_mov_b64_e32 v[46:47], v[232:233]
	v_mov_b64_e32 v[48:49], v[234:235]
	v_mov_b64_e32 v[42:43], v[236:237]
	v_mov_b64_e32 v[44:45], v[238:239]
	v_mov_b64_e32 v[38:39], v[240:241]
	v_mov_b64_e32 v[40:41], v[242:243]
	v_mov_b64_e32 v[34:35], v[244:245]
	v_mov_b64_e32 v[36:37], v[246:247]
	v_add_u32_e32 v58, s36, v50
	v_lshl_add_u64 v[60:61], v[56:57], 0, s[6:7]
	s_movk_i32 s6, 0x7fff
	v_cmp_ge_i32_e64 s[36:37], s6, v58
	s_nop 1
	s_and_saveexec_b64 s[6:7], s[36:37]
	global_load_dwordx4 v[232:235], v[60:61], off offset:-3072
	global_load_dwordx4 v[236:239], v[60:61], off offset:-2048
	global_load_dwordx4 v[240:243], v[60:61], off offset:-1024
	global_load_dwordx4 v[244:247], v[60:61], off
	s_or_b64 exec, exec, s[6:7]
	v_pk_add_f32 v[60:61], v[46:47], v[42:43]
	v_pk_add_f32 v[58:59], v[48:49], v[44:45]
	v_pk_add_f32 v[60:61], v[60:61], v[38:39]
	v_pk_add_f32 v[58:59], v[58:59], v[40:41]
	v_pk_add_f32 v[60:61], v[60:61], v[34:35]
	v_pk_add_f32 v[58:59], v[58:59], v[36:37]
	v_add_f32_e32 v0, v60, v61
	v_add_f32_e32 v0, v58, v0
	v_add_f32_e32 v0, v59, v0
	s_nop 1
	v_add_f32_dpp v0, v0, v0 quad_perm:[1,0,3,2] row_mask:0xf bank_mask:0xf bound_ctrl:1
	s_nop 1
	v_add_f32_dpp v0, v0, v0 quad_perm:[2,3,0,1] row_mask:0xf bank_mask:0xf bound_ctrl:1
	s_nop 1
	v_add_f32_dpp v0, v0, v0 row_half_mirror row_mask:0xf bank_mask:0xf bound_ctrl:1
	s_nop 1
	v_add_f32_dpp v0, v0, v0 row_mirror row_mask:0xf bank_mask:0xf bound_ctrl:1
	v_mov_b32_e32 v51, v0
	s_nop 1
	v_permlane16_swap_b32_e32 v0, v51
	v_add_f32_e32 v0, v0, v51
	v_mov_b32_e32 v51, v0
	s_nop 1
	v_permlane32_swap_b32_e32 v0, v51
	v_add_f32_e32 v51, v0, v51
	v_fmamk_f32 v43, v51, 0xba800000, v43
	v_fmac_f32_e32 v42, 0xba800000, v51
	v_fmamk_f32 v47, v51, 0xba800000, v47
	v_fmac_f32_e32 v46, 0xba800000, v51
	v_fmamk_f32 v45, v51, 0xba800000, v45
	v_fmamk_f32 v44, v51, 0xba800000, v44
	v_pk_mul_f32 v[58:59], v[42:43], v[42:43]
	v_fmamk_f32 v49, v51, 0xba800000, v49
	v_fmamk_f32 v48, v51, 0xba800000, v48
	v_fmamk_f32 v39, v51, 0xba800000, v39
	v_fmac_f32_e32 v38, 0xba800000, v51
	v_pk_mul_f32 v[60:61], v[44:45], v[44:45]
	v_pk_fma_f32 v[58:59], v[46:47], v[46:47], v[58:59]
	v_fmamk_f32 v41, v51, 0xba800000, v41
	v_fmamk_f32 v40, v51, 0xba800000, v40
	v_fmamk_f32 v35, v51, 0xba800000, v35
	v_fmac_f32_e32 v34, 0xba800000, v51
	v_pk_fma_f32 v[60:61], v[48:49], v[48:49], v[60:61]
	v_pk_fma_f32 v[58:59], v[38:39], v[38:39], v[58:59]
	v_fmamk_f32 v37, v51, 0xba800000, v37
	v_fmamk_f32 v36, v51, 0xba800000, v36
	v_pk_fma_f32 v[60:61], v[40:41], v[40:41], v[60:61]
	v_pk_fma_f32 v[58:59], v[34:35], v[34:35], v[58:59]
	v_pk_fma_f32 v[60:61], v[36:37], v[36:37], v[60:61]
	v_add_f32_e32 v0, v58, v59
	v_add_f32_e32 v0, v60, v0
	v_add_f32_e32 v0, v61, v0
	s_nop 1
	v_add_f32_dpp v0, v0, v0 quad_perm:[1,0,3,2] row_mask:0xf bank_mask:0xf bound_ctrl:1
	s_nop 1
	v_add_f32_dpp v0, v0, v0 quad_perm:[2,3,0,1] row_mask:0xf bank_mask:0xf bound_ctrl:1
	s_nop 1
	v_add_f32_dpp v0, v0, v0 row_half_mirror row_mask:0xf bank_mask:0xf bound_ctrl:1
	s_nop 1
	v_add_f32_dpp v0, v0, v0 row_mirror row_mask:0xf bank_mask:0xf bound_ctrl:1
	v_mov_b32_e32 v53, v0
	s_nop 1
	v_permlane16_swap_b32_e32 v0, v53
	v_add_f32_e32 v0, v0, v53
	v_mov_b32_e32 v53, v0
	s_nop 1
	v_permlane32_swap_b32_e32 v0, v53
	v_add_f32_e32 v0, v0, v53
	v_fmamk_f32 v0, v0, 0x3a800000, v178
	v_mul_f32_e32 v53, 0x4b800000, v0
	v_cmp_gt_f32_e64 s[36:37], s85, v0
	s_nop 1
	v_cndmask_b32_e64 v0, v0, v53, s[36:37]
	v_rsq_f32_e32 v0, v0
	s_nop 0
	v_mul_f32_e32 v53, 0x45800000, v0
	v_cndmask_b32_e64 v0, v0, v53, s[36:37]
	s_and_saveexec_b64 s[6:7], vcc
	s_cbranch_execz .LBB0_1564
	v_ashrrev_i32_e32 v53, 31, v52
	v_mul_f32_e32 v58, 0x3a800000, v51
	v_lshl_add_u64 v[60:61], v[52:53], 2, s[38:39]
	v_mov_b32_e32 v59, v0
	flat_store_dwordx2 v[60:61], v[58:59]
	s_branch .LBB0_1564

; DEVI int opaque_tid() { int t = __builtin_amdgcn_workitem_id_x(); asm volatile("" : "+v"(t)); return t; }
; DEVI char* opaque_ptr(char* p) { asm volatile("" : "+s"(p)); return p; }
; DEVI void phase_ln(const Params& p, int L, int which) {
;   const int lane = opaque_tid() & 63, wid = opaque_tid() >> 6;
;   const int gw = blockIdx.x * 4 + wid, nw = gridDim.x * 4;
;   const float* g = p.in[22] + (L * 3 + which) * 1024;
;   const float* bb = p.in[23] + (L * 3 + which) * 1024;
;   char* ws = opaque_ptr(p.ws);
;   bf16* xb = (bf16*)(ws + OFF_XB);
;   float* stats = (float*)(ws + OFF_STATS);
;   const bool final_out = (L == 3 && which == 2);
;   const f32x4 g0 = *(const f32x4*)(g + lane * 4), g1 = *(const f32x4*)(g + 256 + lane * 4), g2 = *(const f32x4*)(g + 512 + lane * 4), g3 = *(const f32x4*)(g + 768 + lane * 4);
;   const f32x4 b0 = *(const f32x4*)(bb + lane * 4), b1 = *(const f32x4*)(bb + 256 + lane * 4), b2 = *(const f32x4*)(bb + 512 + lane * 4), b3 = *(const f32x4*)(bb + 768 + lane * 4);
;   for (int row = gw; row < T_TOK; row += nw) {
;     float* xr = p.out + (long)row * 1024;
;     f32x4 v0 = *(const f32x4*)(xr + lane * 4), v1 = *(const f32x4*)(xr + 256 + lane * 4);
.LBB0_1810:
	s_or_b64 exec, exec, s[18:19]
	v_mov_b32_e32 v2, v154
	v_mov_b32_e32 v0, v154
	s_waitcnt lgkmcnt(0)
	s_barrier
	s_add_i32 s80, s12, 0x400
	v_ashrrev_i32_e32 v0, 6, v0
	v_readlane_b32 s6, v250, 9
	s_add_u32 s16, s16, 0x1000
	v_readlane_b32 s60, v250, 17
	v_add_u32_e32 v50, s6, v0
	s_addc_u32 s17, s17, 0
	s_lshl_b64 s[6:7], s[80:81], 2
	v_readlane_b32 s74, v250, 31
	v_readlane_b32 s75, v250, 32
	s_add_u32 s18, s74, s6
	s_mov_b32 s6, 0x8000
	v_readlane_b32 s62, v250, 19
	s_addc_u32 s19, s75, s7
	s_mov_b64 s[36:37], s[90:91]
	v_cmp_gt_i32_e32 vcc, s6, v50
	v_readlane_b32 s61, v250, 18
	v_readlane_b32 s63, v250, 20
	v_readlane_b32 s64, v250, 21
	v_readlane_b32 s65, v250, 22
	v_readlane_b32 s66, v250, 23
	v_readlane_b32 s67, v250, 24
	v_readlane_b32 s68, v250, 25
	v_readlane_b32 s69, v250, 26
	v_readlane_b32 s70, v250, 27
	v_readlane_b32 s71, v250, 28
	v_readlane_b32 s72, v250, 29
	v_readlane_b32 s73, v250, 30
	s_and_saveexec_b64 s[38:39], vcc
	v_readlane_b32 s62, v248, 28
	v_readlane_b32 s63, v248, 29
	s_cbranch_execz .LBB0_1815
	v_and_b32_e32 v36, 63, v2
	v_lshlrev_b32_e32 v37, 4, v36
	global_load_dwordx4 v[2:5], v37, s[16:17]
	global_load_dwordx4 v[6:9], v37, s[16:17] offset:1024
	global_load_dwordx4 v[10:13], v37, s[16:17] offset:2048
	global_load_dwordx4 v[14:17], v37, s[16:17] offset:3072
	global_load_dwordx4 v[18:21], v37, s[18:19]
	global_load_dwordx4 v[22:25], v37, s[18:19] offset:1024
	global_load_dwordx4 v[26:29], v37, s[18:19] offset:2048
	global_load_dwordx4 v[30:33], v37, s[18:19] offset:3072
	v_ashrrev_i32_e32 v51, 31, v50
	v_lshlrev_b64 v[34:35], 11, v[50:51]
	v_readlane_b32 s6, v249, 41
	v_lshl_or_b32 v34, v36, 3, v34
	v_lshl_add_u64 v[34:35], s[36:37], 0, v[34:35]
	v_lshl_add_u32 v52, v0, 1, s6
	s_mov_b64 s[6:7], 0x22bc000
	v_lshl_add_u64 v[54:55], v[34:35], 0, s[6:7]
	v_lshlrev_b64 v[34:35], 12, v[50:51]
	v_readlane_b32 s6, v249, 45
	s_add_u32 s40, s36, 0x1d6bc000
	v_or_b32_e32 v34, v34, v37
	v_readlane_b32 s7, v249, 46
	s_addc_u32 s41, s37, 0
	v_cmp_eq_u32_e32 vcc, 0, v36
	v_lshl_add_u64 v[56:57], s[6:7], 0, v[34:35]
	global_load_dwordx4 v[232:235], v[56:57], off offset:-3072
	global_load_dwordx4 v[236:239], v[56:57], off offset:-2048
	global_load_dwordx4 v[240:243], v[56:57], off offset:-1024
	global_load_dwordx4 v[244:247], v[56:57], off
	s_mov_b64 s[50:51], 0
	s_branch .LBB0_1813

; DEVI void phase_ln(const Params& p, int L, int which) {
;     ...
;   for (int row = gw; row < T_TOK; row += nw) {
;     float* xr = p.out + (long)row * 1024;
;     f32x4 v0 = *(const f32x4*)(xr + lane * 4), v1 = *(const f32x4*)(xr + 256 + lane * 4);
;     f32x4 v2 = *(const f32x4*)(xr + 512 + lane * 4), v3 = *(const f32x4*)(xr + 768 + lane * 4);
;     f32x4 sv = v0 + v1 + v2 + v3;
;     float s = sv[0] + sv[1] + sv[2] + sv[3];
;     s = wave_sum(s);
;     const float mu = s * (1.f / 1024.f);
;     v0 -= mu; v1 -= mu; v2 -= mu; v3 -= mu;
;     f32x4 qv = v0 * v0 + v1 * v1 + v2 * v2 + v3 * v3;
;     float q = qv[0] + qv[1] + qv[2] + qv[3];
;     q = wave_sum(q);
;     const float rstd = rsqrtf(q * (1.f / 1024.f) + 1e-5f);
;     if (lane == 0) { stats[row * 2] = mu; stats[row * 2 + 1] = rstd; }
.LBB0_1813:
	s_waitcnt vmcnt(0)
	v_readlane_b32 s36, v249, 50
	v_readlane_b32 s6, v249, 52
	v_readlane_b32 s7, v249, 53
	v_mov_b64_e32 v[46:47], v[232:233]
	v_mov_b64_e32 v[48:49], v[234:235]
	v_mov_b64_e32 v[42:43], v[236:237]
	v_mov_b64_e32 v[44:45], v[238:239]
	v_mov_b64_e32 v[38:39], v[240:241]
	v_mov_b64_e32 v[40:41], v[242:243]
	v_mov_b64_e32 v[34:35], v[244:245]
	v_mov_b64_e32 v[36:37], v[246:247]
	v_add_u32_e32 v58, s36, v50
	v_lshl_add_u64 v[60:61], v[56:57], 0, s[6:7]
	s_movk_i32 s6, 0x7fff
	v_cmp_ge_i32_e64 s[36:37], s6, v58
	s_nop 1
	s_and_saveexec_b64 s[6:7], s[36:37]
	global_load_dwordx4 v[232:235], v[60:61], off offset:-3072
	global_load_dwordx4 v[236:239], v[60:61], off offset:-2048
	global_load_dwordx4 v[240:243], v[60:61], off offset:-1024
	global_load_dwordx4 v[244:247], v[60:61], off
	s_or_b64 exec, exec, s[6:7]
	v_pk_add_f32 v[60:61], v[46:47], v[42:43]
	v_pk_add_f32 v[58:59], v[48:49], v[44:45]
	v_pk_add_f32 v[60:61], v[60:61], v[38:39]
	v_pk_add_f32 v[58:59], v[58:59], v[40:41]
	v_pk_add_f32 v[60:61], v[60:61], v[34:35]
	v_pk_add_f32 v[58:59], v[58:59], v[36:37]
	v_add_f32_e32 v0, v60, v61
	v_add_f32_e32 v0, v58, v0
	v_add_f32_e32 v0, v59, v0
	s_nop 1
	v_add_f32_dpp v0, v0, v0 quad_perm:[1,0,3,2] row_mask:0xf bank_mask:0xf bound_ctrl:1
	s_nop 1
	v_add_f32_dpp v0, v0, v0 quad_perm:[2,3,0,1] row_mask:0xf bank_mask:0xf bound_ctrl:1
	s_nop 1
	v_add_f32_dpp v0, v0, v0 row_half_mirror row_mask:0xf bank_mask:0xf bound_ctrl:1
	s_nop 1
	v_add_f32_dpp v0, v0, v0 row_mirror row_mask:0xf bank_mask:0xf bound_ctrl:1
	v_mov_b32_e32 v51, v0
	s_nop 1
	v_permlane16_swap_b32_e32 v0, v51
	v_add_f32_e32 v0, v0, v51
	v_mov_b32_e32 v51, v0
	s_nop 1
	v_permlane32_swap_b32_e32 v0, v51
	v_add_f32_e32 v51, v0, v51
	v_fmamk_f32 v43, v51, 0xba800000, v43
	v_fmac_f32_e32 v42, 0xba800000, v51
	v_fmamk_f32 v47, v51, 0xba800000, v47
	v_fmac_f32_e32 v46, 0xba800000, v51
	v_fmamk_f32 v45, v51, 0xba800000, v45
	v_fmamk_f32 v44, v51, 0xba800000, v44
	v_pk_mul_f32 v[58:59], v[42:43], v[42:43]
	v_fmamk_f32 v49, v51, 0xba800000, v49
	v_fmamk_f32 v48, v51, 0xba800000, v48
	v_fmamk_f32 v39, v51, 0xba800000, v39
	v_fmac_f32_e32 v38, 0xba800000, v51
	v_pk_mul_f32 v[60:61], v[44:45], v[44:45]
	v_pk_fma_f32 v[58:59], v[46:47], v[46:47], v[58:59]
	v_fmamk_f32 v41, v51, 0xba800000, v41
	v_fmamk_f32 v40, v51, 0xba800000, v40
	v_fmamk_f32 v35, v51, 0xba800000, v35
	v_fmac_f32_e32 v34, 0xba800000, v51
	v_pk_fma_f32 v[60:61], v[48:49], v[48:49], v[60:61]
	v_pk_fma_f32 v[58:59], v[38:39], v[38:39], v[58:59]
	v_fmamk_f32 v37, v51, 0xba800000, v37
	v_fmamk_f32 v36, v51, 0xba800000, v36
	v_pk_fma_f32 v[60:61], v[40:41], v[40:41], v[60:61]
	v_pk_fma_f32 v[58:59], v[34:35], v[34:35], v[58:59]
	v_pk_fma_f32 v[60:61], v[36:37], v[36:37], v[60:61]
	v_add_f32_e32 v0, v58, v59
	v_add_f32_e32 v0, v60, v0
	v_add_f32_e32 v0, v61, v0
	s_nop 1
	v_add_f32_dpp v0, v0, v0 quad_perm:[1,0,3,2] row_mask:0xf bank_mask:0xf bound_ctrl:1
	s_nop 1
	v_add_f32_dpp v0, v0, v0 quad_perm:[2,3,0,1] row_mask:0xf bank_mask:0xf bound_ctrl:1
	s_nop 1
	v_add_f32_dpp v0, v0, v0 row_half_mirror row_mask:0xf bank_mask:0xf bound_ctrl:1
	s_nop 1
	v_add_f32_dpp v0, v0, v0 row_mirror row_mask:0xf bank_mask:0xf bound_ctrl:1
	v_mov_b32_e32 v53, v0
	s_nop 1
	v_permlane16_swap_b32_e32 v0, v53
	v_add_f32_e32 v0, v0, v53
	v_mov_b32_e32 v53, v0
	s_nop 1
	v_permlane32_swap_b32_e32 v0, v53
	v_add_f32_e32 v0, v0, v53
	v_fmamk_f32 v0, v0, 0x3a800000, v178
	v_mul_f32_e32 v53, 0x4b800000, v0
	v_cmp_gt_f32_e64 s[36:37], s85, v0
	s_nop 1
	v_cndmask_b32_e64 v0, v0, v53, s[36:37]
	v_rsq_f32_e32 v0, v0
	s_nop 0
	v_mul_f32_e32 v53, 0x45800000, v0
	v_cndmask_b32_e64 v0, v0, v53, s[36:37]
	s_and_saveexec_b64 s[6:7], vcc
	s_cbranch_execz .LBB0_1812
	v_ashrrev_i32_e32 v53, 31, v52
	v_mul_f32_e32 v58, 0x3a800000, v51
	v_lshl_add_u64 v[60:61], v[52:53], 2, s[40:41]
	v_mov_b32_e32 v59, v0
	flat_store_dwordx2 v[60:61], v[58:59]
	s_branch .LBB0_1812
